# scan: waves 4-7 compute the next chunk's cumulative log-decay during S3 (idle slot after B2) instead of in S1c
# speedup vs baseline: 1.0028x; 1.0028x over previous
; #define LAS __attribute__((address_space(3)))
; __device__ __forceinline__ void scan_pass1(const ScanP& sp, int b, int h, int seg, LAS unsigned char* lds) {
;     ...
;         __syncthreads();
;         {
;             const f32x4 r4 = *(const LAS f32x4*)(stash + tid * 12), v4 = *(const LAS f32x4*)(stash + tid * 12 + 4), kp = *(const LAS f32x4*)(stash + tid * 12 + 8);
;             f32x4 cl = {0.f, 0.f, 0.f, 0.f};
; #pragma unroll 2
;             for (int s4 = 0; s4 < w; ++s4) {
;                 const LAS float* lp_ = lwS + (4 * s4) * 64 + j4;
;                 const f32x4 x0 = *(const LAS f32x4*)lp_, x1 = *(const LAS f32x4*)(lp_ + 64), x2 = *(const LAS f32x4*)(lp_ + 128), x3 = *(const LAS f32x4*)(lp_ + 192);
;                 cl += (x0 + x1) + (x2 + x3);
;             }
; #pragma unroll
;             for (int q = 0; q < 4; ++q) { const int s = 4 * w + q; const f32x4 x = *(const LAS f32x4*)(lwS + s * 64 + j4); if (s <= tt) cl += x; }
.Ls1c_noprio:
	ds_read_b128 v[76:79], v190
	ds_read_b128 v[68:71], v190 offset:16
	ds_read_b128 v[72:75], v190 offset:32
	s_cmp_eq_u32 s83, 0
	s_cbranch_scc1 .Lcs_do
	s_and_b64 vcc, exec, s[56:57]
	s_cbranch_vccnz .Lcs_have
.Lcs_do:
	s_andn2_b64 vcc, exec, s[98:99]
	s_cbranch_vccnz .LBB0_258
	s_andn2_b64 vcc, exec, s[58:59]
	s_cbranch_vccnz .LBB0_259
	v_mov_b32_e32 v80, 0
	s_mov_b32 s0, 0
	v_mov_b32_e32 v0, v183
	v_mov_b32_e32 v81, v80
	v_mov_b32_e32 v82, v80
	v_mov_b32_e32 v83, v80

; __device__ __forceinline__ void scan_pass1(const ScanP& sp, int b, int h, int seg, LAS unsigned char* lds) {
;     ...
;             f32x4 ein, eex, einv;
; #pragma unroll
;             for (int e = 0; e < 4; ++e) { ein[e] = ex2(cl[e]); eex[e] = ex2(cl[e] - lw[e]); einv[e] = __builtin_amdgcn_rcpf(ein[e]); }
;             const f32x4 kkt = kkn * eex, rt = r4 * ein, kh = kp * einv, bh = bb * einv;
;             u32x2 o;
;             o.x = pk2(kkt[0], kkt[1]); o.y = pk2(kkt[2], kkt[3]); *(LAS u32x2*)(lds + O_KK + (tt * 72 + j4) * 2) = o;
;             o.x = pk2(rt[0], rt[1]); o.y = pk2(rt[2], rt[3]); *(LAS u32x2*)(lds + O_R + (tt * 72 + j4) * 2) = o;
;             o.x = pk2(kh[0], kh[1]); o.y = pk2(kh[2], kh[3]); *(LAS u32x2*)(lds + O_K + (tt * 72 + j4) * 2) = o;
;             const unsigned k01 = o.x, k23 = o.y;
;             o.x = pk2(bh[0], bh[1]); o.y = pk2(bh[2], bh[3]); *(LAS u32x2*)(lds + O_B + (tt * 72 + j4) * 2) = o;
;             const unsigned nb01 = pk2(-bh[0], -bh[1]), nb23 = pk2(-bh[2], -bh[3]);
;             const unsigned v01 = pk2(v4[0], v4[1]), v23 = pk2(v4[2], v4[3]);
;             LAS unsigned short* kt = (LAS unsigned short*)(lds + O_KT) + j4 * 40 + tt;
;             kt[0] = (unsigned short)(k01 & 0xffffu); kt[40] = (unsigned short)(k01 >> 16); kt[80] = (unsigned short)(k23 & 0xffffu); kt[120] = (unsigned short)(k23 >> 16);
;             LAS unsigned short* bt = (LAS unsigned short*)(lds + O_BT) + j4 * 40 + tt;
;             bt[0] = (unsigned short)(nb01 & 0xffffu); bt[40] = (unsigned short)(nb01 >> 16); bt[80] = (unsigned short)(nb23 & 0xffffu); bt[120] = (unsigned short)(nb23 >> 16);
;             LAS unsigned short* vt = (LAS unsigned short*)(lds + O_VT) + j4 * 40 + tt;
;             vt[0] = (unsigned short)(v01 & 0xffffu); vt[40] = (unsigned short)(v01 >> 16); vt[80] = (unsigned short)(v23 & 0xffffu); vt[120] = (unsigned short)(v23 >> 16);
;             if (tt == 31) *(LAS f32x4*)(gam + j4) = ein;
;         }
;         __syncthreads();
;     ...
;         } else {
;             const int job = w - 4;
;             const int oa = (job == 0 || job == 2) ? O_K : O_B, ob = (job < 2) ? O_KK : O_R;
;             f32x16 Z;
; #pragma unroll
;             for (int i = 0; i < 16; ++i) Z[i] = 0.f;
; #pragma unroll
;             for (int ks = 0; ks < 4; ++ks) {
;                 const int off = (ln * 72 + ks * 16 + hh * 8) * 2;
.Lcs_have:
	v_sub_f32_e32 v0, v80, v100
	v_exp_f32_e32 v104, v80
	v_exp_f32_e32 v105, v81
	v_exp_f32_e32 v2, v0
	v_sub_f32_e32 v0, v81, v101
	v_exp_f32_e32 v106, v82
	v_exp_f32_e32 v107, v83
	v_exp_f32_e32 v3, v0
	v_sub_f32_e32 v0, v82, v102
	v_exp_f32_e32 v82, v0
	v_sub_f32_e32 v0, v83, v103
	v_exp_f32_e32 v83, v0
	v_rcp_f32_e32 v80, v104
	v_rcp_f32_e32 v81, v105
	v_rcp_f32_e32 v110, v106
	v_rcp_f32_e32 v111, v107
	v_pk_mul_f32 v[82:83], v[132:133], v[82:83]
	v_pk_mul_f32 v[2:3], v[130:131], v[2:3]
	s_waitcnt lgkmcnt(0)
	v_pk_mul_f32 v[78:79], v[78:79], v[106:107]
	v_pk_mul_f32 v[76:77], v[76:77], v[104:105]
	v_pk_mul_f32 v[74:75], v[74:75], v[110:111]
	v_pk_mul_f32 v[72:73], v[72:73], v[80:81]
	v_pk_mul_f32 v[110:111], v[136:137], v[110:111]
	v_pk_mul_f32 v[80:81], v[134:135], v[80:81]
	v_cvt_pk_bf16_f32 v2, v2, v3
	v_cvt_pk_bf16_f32 v3, v82, v83
	v_add_u32_e32 v0, 0, v163
	v_cvt_pk_bf16_f32 v76, v76, v77
	v_cvt_pk_bf16_f32 v77, v78, v79
	ds_write2st64_b64 v0, v[2:3], v[76:77] offset0:64 offset1:73
	v_cvt_pk_bf16_f32 v2, v72, v73
	v_cvt_pk_bf16_f32 v3, v74, v75
	v_cvt_pk_bf16_f32 v72, v80, v81
	v_cvt_pk_bf16_f32 v73, v110, v111
	ds_write2st64_b64 v0, v[2:3], v[72:73] offset0:82 offset1:91
	v_xor_b32_e32 v0, 0x80000000, v81
	v_xor_b32_e32 v72, 0x80000000, v80
	v_cvt_pk_bf16_f32 v0, v72, v0
	v_xor_b32_e32 v72, 0x80000000, v110
	v_xor_b32_e32 v73, 0x80000000, v111
	v_cvt_pk_bf16_f32 v72, v72, v73
	v_cvt_pk_bf16_f32 v68, v68, v69
	v_cvt_pk_bf16_f32 v69, v70, v71
	v_mov_b32_e32 v250, v0
	v_mov_b32_e32 v251, v72
	v_lshlrev_b32_e32 v245, 3, v210
	v_and_b32_e32 v245, 48, v245
	v_mov_b32_e32 v246, v245
	v_mad_u32_u24 v247, v246, 5, v164
	v_lshrrev_b64 v[230:231], v246, v[2:3]
	v_lshrrev_b64 v[232:233], v246, v[250:251]
	v_lshrrev_b64 v[234:235], v246, v[68:69]
	ds_write_b16 v247, v230 offset:51200
	ds_write_b16 v247, v232 offset:56320
	ds_write_b16 v247, v234 offset:61440
	v_add_u32_e32 v246, 16, v245
	v_and_b32_e32 v246, 48, v246
	v_mad_u32_u24 v247, v246, 5, v164
	v_lshrrev_b64 v[230:231], v246, v[2:3]
	v_lshrrev_b64 v[232:233], v246, v[250:251]
	v_lshrrev_b64 v[234:235], v246, v[68:69]
	ds_write_b16 v247, v230 offset:51200
	ds_write_b16 v247, v232 offset:56320
	ds_write_b16 v247, v234 offset:61440
	v_add_u32_e32 v246, 32, v245
	v_and_b32_e32 v246, 48, v246
	v_mad_u32_u24 v247, v246, 5, v164
	v_lshrrev_b64 v[230:231], v246, v[2:3]
	v_lshrrev_b64 v[232:233], v246, v[250:251]
	v_lshrrev_b64 v[234:235], v246, v[68:69]
	ds_write_b16 v247, v230 offset:51200
	ds_write_b16 v247, v232 offset:56320
	ds_write_b16 v247, v234 offset:61440
	v_add_u32_e32 v246, 48, v245
	v_and_b32_e32 v246, 48, v246
	v_mad_u32_u24 v247, v246, 5, v164
	v_lshrrev_b64 v[230:231], v246, v[2:3]
	v_lshrrev_b64 v[232:233], v246, v[250:251]
	v_lshrrev_b64 v[234:235], v246, v[68:69]
	ds_write_b16 v247, v230 offset:51200
	ds_write_b16 v247, v232 offset:56320
	ds_write_b16 v247, v234 offset:61440
	s_and_saveexec_b64 s[0:1], s[52:53]
	ds_write_b128 v165, v[104:107]
	s_or_b64 exec, exec, s[0:1]
	v_mul_u32_u24_e32 v0, 0x90, v189
	s_andn2_b64 vcc, exec, s[56:57]
	s_mov_b64 s[0:1], -1
	s_waitcnt lgkmcnt(0)
	s_setprio 0
	s_barrier
	s_cbranch_vccnz .LBB0_284
	v_lshl_add_u32 v2, v188, 4, v0
	v_add_u32_e32 v3, s65, v2
	v_add_u32_e32 v2, s77, v2
	ds_read_b128 v[68:71], v3
	ds_read_b128 v[72:75], v2
	ds_read_b128 v[104:107], v3 offset:32
	ds_read_b128 v[110:113], v2 offset:32
	ds_read_b128 v[230:233], v3 offset:64
	ds_read_b128 v[234:237], v2 offset:64
	ds_read_b128 v[238:241], v3 offset:96
	ds_read_b128 v[242:245], v2 offset:96
	s_mov_b64 s[78:79], -1
	s_and_b64 vcc, exec, s[72:73]
	s_waitcnt lgkmcnt(6)
	v_mfma_f32_32x32x16_bf16 v[68:83], v[68:71], v[72:75], 0
	s_waitcnt lgkmcnt(4)
	v_mfma_f32_32x32x16_bf16 v[68:83], v[104:107], v[110:113], v[68:83]
	s_waitcnt lgkmcnt(2)
	v_mfma_f32_32x32x16_bf16 v[68:83], v[230:233], v[234:237], v[68:83]
	v_lshlrev_b32_e32 v2, 2, v188
	v_or_b32_e32 v117, 2, v2
	v_or_b32_e32 v116, 3, v2
	v_add_u32_e32 v115, 8, v2
	v_add_u32_e32 v109, 10, v2
	v_add_u32_e32 v3, 11, v2
	s_waitcnt lgkmcnt(0)
	v_mfma_f32_32x32x16_bf16 v[68:83], v[238:241], v[242:245], v[68:83]
	v_add_u32_e32 v113, 9, v2
	v_add_u32_e32 v111, 16, v2
	v_add_u32_e32 v106, 17, v2
	v_add_u32_e32 v110, 18, v2
	v_add_u32_e32 v104, 19, v2
	v_add_u32_e32 v114, 24, v2
	v_add_u32_e32 v112, 25, v2
	v_add_u32_e32 v107, 26, v2
	v_add_u32_e32 v105, 27, v2
	v_cmp_lt_i32_e64 s[40:41], v2, v189
	v_cmp_lt_i32_e64 s[50:51], v117, v189
	v_cmp_lt_i32_e64 s[48:49], v116, v189
	v_cmp_lt_i32_e64 s[46:47], v115, v189
	v_cmp_lt_i32_e64 s[44:45], v113, v189
	v_cmp_lt_i32_e64 s[42:43], v109, v189
	v_cmp_lt_i32_e64 s[38:39], v3, v189
	v_cmp_lt_i32_e64 s[36:37], v111, v189
	v_cmp_lt_i32_e64 s[34:35], v106, v189
	v_cmp_lt_i32_e64 s[30:31], v110, v189
	v_cmp_lt_i32_e64 s[28:29], v104, v189
	v_cmp_lt_i32_e64 s[26:27], v114, v189
	v_cmp_lt_i32_e64 s[24:25], v112, v189
	v_cmp_lt_i32_e64 s[22:23], v107, v189
	v_cmp_lt_i32_e64 s[0:1], v105, v189
	s_cbranch_vccz .LBB0_271
; #define LAS __attribute__((address_space(3)))
; __device__ __forceinline__ unsigned pk2(float lo, float hi) { f32x2 v = {lo, hi}; bf16x2_t b = __builtin_convertvector(v, bf16x2_t); return __builtin_bit_cast(unsigned, b); }
; __device__ __forceinline__ void scan_pass1(const ScanP& sp, int b, int h, int seg, LAS unsigned char* lds) {
;     ...
;                 const int oo = (job == 0) ? O_MK : (job == 2) ? O_NK : O_NB;
; #pragma unroll
;                 for (int g = 0; g < 4; ++g) {
;                     float z[4];
; #pragma unroll
;                     for (int e = 0; e < 4; ++e) {
;                         const int s = 8 * g + 4 * hh + e;
;                         const bool keep = (job == 0) ? (s < ln) : (s <= ln);
;                         float v = keep ? Z[4 * g + e] : 0.f; if (job == 3) v = -v; z[e] = v;
;                     }
;                     u32x2 o; o.x = pk2(z[0], z[1]); o.y = pk2(z[2], z[3]);
;                     *(LAS u32x2*)(lds + oo + (ln * 40 + 8 * g + 4 * hh) * 2) = o;
;                 }
	v_lshlrev_b32_e32 v118, 3, v188
	v_mul_u32_u24_e32 v119, 0x50, v189
	v_cmp_le_i32_e32 vcc, v2, v189
	v_add3_u32 v121, s33, v118, v119
	v_cndmask_b32_e64 v118, 0, 1, s[40:41]
	v_cndmask_b32_e64 v119, 0, 1, vcc
	v_cndmask_b32_e64 v118, v119, v118, s[4:5]
	v_and_b32_e32 v118, 1, v118
	v_cmp_eq_u32_e32 vcc, 1, v118
	v_or_b32_e32 v119, v2, v166
	v_cndmask_b32_e64 v123, 0, 1, s[50:51]
	v_cndmask_b32_e32 v118, 0, v68, vcc
	v_cmp_gt_i32_e32 vcc, v189, v119
	v_cndmask_b32_e64 v118, v118, -v118, s[74:75]
	s_mov_b64 s[78:79], 0
	v_cndmask_b32_e32 v119, 0, v69, vcc
	v_cmp_le_i32_e32 vcc, v117, v189
	v_cndmask_b32_e64 v119, v119, -v119, s[74:75]
	v_cvt_pk_bf16_f32 v118, v118, v119
	v_cndmask_b32_e64 v150, 0, 1, vcc
	v_cndmask_b32_e64 v123, v150, v123, s[4:5]
	v_and_b32_e32 v123, 1, v123
	v_cmp_eq_u32_e32 vcc, 1, v123
	v_cndmask_b32_e64 v150, 0, 1, s[48:49]
	s_nop 0
	v_cndmask_b32_e32 v123, 0, v70, vcc
	v_cmp_le_i32_e32 vcc, v116, v189
	v_cndmask_b32_e64 v123, v123, -v123, s[74:75]
	s_nop 0
	v_cndmask_b32_e64 v151, 0, 1, vcc
	v_cndmask_b32_e64 v150, v151, v150, s[4:5]
	v_and_b32_e32 v150, 1, v150
	v_cmp_eq_u32_e32 vcc, 1, v150
	s_nop 1
	v_cndmask_b32_e32 v150, 0, v71, vcc
	v_cndmask_b32_e64 v150, v150, -v150, s[74:75]
	v_cmp_le_i32_e32 vcc, v115, v189
	v_cvt_pk_bf16_f32 v119, v123, v150
	v_cndmask_b32_e64 v123, 0, 1, s[46:47]
	v_cndmask_b32_e64 v150, 0, 1, vcc
	v_cndmask_b32_e64 v123, v150, v123, s[4:5]
	v_and_b32_e32 v123, 1, v123
	v_cmp_eq_u32_e32 vcc, 1, v123
	v_cndmask_b32_e64 v150, 0, 1, s[44:45]
	s_nop 0
	v_cndmask_b32_e32 v123, 0, v72, vcc
	v_cmp_le_i32_e32 vcc, v113, v189
	v_cndmask_b32_e64 v123, v123, -v123, s[74:75]
	s_nop 0
	v_cndmask_b32_e64 v151, 0, 1, vcc
	v_cndmask_b32_e64 v150, v151, v150, s[4:5]
	v_and_b32_e32 v150, 1, v150
	v_cmp_eq_u32_e32 vcc, 1, v150
	v_cndmask_b32_e64 v151, 0, 1, s[42:43]
	s_nop 0
	v_cndmask_b32_e32 v150, 0, v73, vcc
	v_cmp_le_i32_e32 vcc, v109, v189
	v_cndmask_b32_e64 v150, v150, -v150, s[74:75]
	v_cvt_pk_bf16_f32 v150, v123, v150
	v_cndmask_b32_e64 v152, 0, 1, vcc
	v_cndmask_b32_e64 v151, v152, v151, s[4:5]
	v_and_b32_e32 v151, 1, v151
	v_cmp_eq_u32_e32 vcc, 1, v151
	v_cndmask_b32_e64 v152, 0, 1, s[38:39]
	s_nop 0
	v_cndmask_b32_e32 v151, 0, v74, vcc
	v_cmp_le_i32_e32 vcc, v3, v189
	v_cndmask_b32_e64 v151, v151, -v151, s[74:75]
	s_nop 0
	v_cndmask_b32_e64 v153, 0, 1, vcc
	v_cndmask_b32_e64 v152, v153, v152, s[4:5]
	v_and_b32_e32 v152, 1, v152
	v_cmp_eq_u32_e32 vcc, 1, v152
	s_nop 1
	v_cndmask_b32_e32 v152, 0, v75, vcc
	v_cndmask_b32_e64 v152, v152, -v152, s[74:75]
	v_cvt_pk_bf16_f32 v151, v151, v152
	v_cmp_le_i32_e32 vcc, v111, v189
	ds_write2_b64 v121, v[118:119], v[150:151] offset1:2
	v_cndmask_b32_e64 v118, 0, 1, s[36:37]
	v_cndmask_b32_e64 v119, 0, 1, vcc
	v_cndmask_b32_e64 v118, v119, v118, s[4:5]
	v_and_b32_e32 v118, 1, v118
	v_cmp_eq_u32_e32 vcc, 1, v118
	v_cndmask_b32_e64 v119, 0, 1, s[34:35]
	s_nop 0
	v_cndmask_b32_e32 v118, 0, v76, vcc
	v_cmp_le_i32_e32 vcc, v106, v189
	v_cndmask_b32_e64 v118, v118, -v118, s[74:75]
	s_nop 0
	v_cndmask_b32_e64 v123, 0, 1, vcc
	v_cndmask_b32_e64 v119, v123, v119, s[4:5]
	v_and_b32_e32 v119, 1, v119
	v_cmp_eq_u32_e32 vcc, 1, v119
	v_cndmask_b32_e64 v123, 0, 1, s[30:31]
	s_nop 0
	v_cndmask_b32_e32 v119, 0, v77, vcc
	v_cmp_le_i32_e32 vcc, v110, v189
	v_cndmask_b32_e64 v119, v119, -v119, s[74:75]
	v_cvt_pk_bf16_f32 v118, v118, v119
	v_cndmask_b32_e64 v150, 0, 1, vcc
	v_cndmask_b32_e64 v123, v150, v123, s[4:5]
	v_and_b32_e32 v123, 1, v123
	v_cmp_eq_u32_e32 vcc, 1, v123
	v_cndmask_b32_e64 v150, 0, 1, s[28:29]
	s_nop 0
	v_cndmask_b32_e32 v123, 0, v78, vcc
	v_cmp_le_i32_e32 vcc, v104, v189
	v_cndmask_b32_e64 v123, v123, -v123, s[74:75]
	s_nop 0
	v_cndmask_b32_e64 v151, 0, 1, vcc
	v_cndmask_b32_e64 v150, v151, v150, s[4:5]
	v_and_b32_e32 v150, 1, v150
	v_cmp_eq_u32_e32 vcc, 1, v150
	s_nop 1
	v_cndmask_b32_e32 v150, 0, v79, vcc
	v_cndmask_b32_e64 v150, v150, -v150, s[74:75]
	v_cmp_le_i32_e32 vcc, v114, v189
	v_cvt_pk_bf16_f32 v119, v123, v150
	v_cndmask_b32_e64 v123, 0, 1, s[26:27]
	v_cndmask_b32_e64 v150, 0, 1, vcc
	v_cndmask_b32_e64 v123, v150, v123, s[4:5]
	v_and_b32_e32 v123, 1, v123
	v_cmp_eq_u32_e32 vcc, 1, v123
	v_cndmask_b32_e64 v150, 0, 1, s[24:25]
	s_nop 0
	v_cndmask_b32_e32 v123, 0, v80, vcc
	v_cmp_le_i32_e32 vcc, v112, v189
	v_cndmask_b32_e64 v123, v123, -v123, s[74:75]
	s_nop 0
	v_cndmask_b32_e64 v151, 0, 1, vcc
	v_cndmask_b32_e64 v150, v151, v150, s[4:5]
	v_and_b32_e32 v150, 1, v150
	v_cmp_eq_u32_e32 vcc, 1, v150
	v_cndmask_b32_e64 v151, 0, 1, s[22:23]
	s_nop 0
	v_cndmask_b32_e32 v150, 0, v81, vcc
	v_cmp_le_i32_e32 vcc, v107, v189
	v_cndmask_b32_e64 v150, v150, -v150, s[74:75]
	v_cvt_pk_bf16_f32 v150, v123, v150
	v_cndmask_b32_e64 v152, 0, 1, vcc
	v_cndmask_b32_e64 v151, v152, v151, s[4:5]
	v_and_b32_e32 v151, 1, v151
	v_cmp_eq_u32_e32 vcc, 1, v151
	v_cndmask_b32_e64 v152, 0, 1, s[0:1]
	s_nop 0
	v_cndmask_b32_e32 v151, 0, v82, vcc
	v_cmp_le_i32_e32 vcc, v105, v189
	v_cndmask_b32_e64 v151, v151, -v151, s[74:75]
	s_nop 0
	v_cndmask_b32_e64 v153, 0, 1, vcc
	v_cndmask_b32_e64 v152, v153, v152, s[4:5]
	v_and_b32_e32 v152, 1, v152
	v_cmp_eq_u32_e32 vcc, 1, v152
	s_nop 1
	v_cndmask_b32_e32 v152, 0, v83, vcc
	v_cndmask_b32_e64 v152, v152, -v152, s[74:75]
	v_cvt_pk_bf16_f32 v151, v151, v152
	ds_write2_b64 v121, v[118:119], v[150:151] offset0:4 offset1:6

; #define LAS __attribute__((address_space(3)))
; #define MFMA32(a, b, c) __builtin_amdgcn_mfma_f32_32x32x16_bf16((a), (b), (c), 0, 0, 0)
; __device__ __forceinline__ int crow(int r, int hi) { return (r & 3) + 8 * (r >> 2) + 4 * hi; }
; __device__ __forceinline__ void scan_pass1(const ScanP& sp, int b, int h, int seg, LAS unsigned char* lds) {
;     ...
;             for (int s4 = 0; s4 < w; ++s4) {
;                 const LAS float* lp_ = lwS + (4 * s4) * 64 + j4;
;                 const f32x4 x0 = *(const LAS f32x4*)lp_, x1 = *(const LAS f32x4*)(lp_ + 64), x2 = *(const LAS f32x4*)(lp_ + 128), x3 = *(const LAS f32x4*)(lp_ + 192);
;                 cl += (x0 + x1) + (x2 + x3);
;             }
; #pragma unroll
;             for (int q = 0; q < 4; ++q) { const int s = 4 * w + q; const f32x4 x = *(const LAS f32x4*)(lwS + s * 64 + j4); if (s <= tt) cl += x; }
;     ...
;             for (int jb = 0; jb < 2; ++jb) {
;                 if (isH) {
; #pragma unroll
;                     for (int ks = 0; ks < 2; ++ks) Hacc[jb] = MFMA32(*(const LAS bf16x8*)(lds + O_KT + ((32 * jb + ln) * 40 + ks * 16 + hh * 8) * 2), vfr[ks], Hacc[jb]);
;                 }
; #pragma unroll
;                 for (int s = 0; s < 2; ++s) Hacc[jb] = MFMA32(ld_krow(lds + O_BT + ((32 * jb + ln) * 40 + 16 * s + 4 * hh) * 2), ab[s], Hacc[jb]);
; #pragma unroll
;                 for (int g = 0; g < 4; ++g) {
;                     const f32x4 gv = *(const LAS f32x4*)(gam + 32 * jb + 8 * g + 4 * hh);
;                     Hacc[jb][4 * g] *= gv[0]; Hacc[jb][4 * g + 1] *= gv[1]; Hacc[jb][4 * g + 2] *= gv[2]; Hacc[jb][4 * g + 3] *= gv[3];
;                 }
;             }
;             LAS float* ob = isH ? yb : qb;
; #pragma unroll
;             for (int r = 0; r < 16; ++r) ob[crow(r, hh) * 64 + icol] = P2[r];
.LBB0_314:
	s_waitcnt lgkmcnt(0)
	v_pk_mul_f32 v[24:25], v[24:25], v[76:77]
	v_lshl_add_u32 v76, v123, 1, 0
	v_pk_mul_f32 v[20:21], v[20:21], v[80:81]
	v_add_u32_e32 v80, 0xe000, v76
	v_pk_mul_f32 v[26:27], v[26:27], v[78:79]
	v_pk_mul_f32 v[22:23], v[22:23], v[82:83]
	ds_read2_b64 v[76:79], v80 offset0:192 offset1:194
	ds_read2_b64 v[80:83], v80 offset0:196 offset1:198
	s_waitcnt lgkmcnt(0)
	v_mfma_f32_32x32x16_bf16 v[4:19], v[76:79], v[68:71], v[4:19]
	v_mul_f32_e64 v34, v34, v118
	v_mul_f32_e64 v35, v35, v119
	v_mul_f32_e64 v30, v30, v114
	v_mul_f32_e64 v31, v31, v115
	v_mul_f32_e64 v32, v32, v116
	v_mul_f32_e64 v33, v33, v117
	v_pk_mul_f32 v[28:29], v[28:29], v[112:113]
	v_mfma_f32_32x32x16_bf16 v[52:67], v[104:107], v[68:71], v[52:67]
	v_lshlrev_b32_e32 v68, 2, v121
	v_lshlrev_b32_e32 v69, 10, v188
	v_add3_u32 v68, s80, v68, v69
	v_mfma_f32_32x32x16_bf16 v[4:19], v[80:83], v[72:75], v[4:19]
	ds_read_b128 v[76:79], v138 offset:128
	ds_read_b128 v[80:83], v138 offset:160
	ds_read_b128 v[112:115], v138 offset:192
	ds_read_b128 v[116:119], v138 offset:224
	v_mfma_f32_32x32x16_bf16 v[52:67], v[108:111], v[72:75], v[52:67]
	s_waitcnt lgkmcnt(0)
	s_nop 5
	v_mul_f32_e64 v18, v18, v118
	v_mul_f32_e64 v19, v19, v119
	v_mul_f32_e64 v16, v16, v116
	v_mul_f32_e64 v17, v17, v117
	v_pk_mul_f32 v[14:15], v[14:15], v[114:115]
	v_pk_mul_f32 v[12:13], v[12:13], v[112:113]
	v_pk_mul_f32 v[10:11], v[10:11], v[82:83]
	v_pk_mul_f32 v[8:9], v[8:9], v[80:81]
	v_pk_mul_f32 v[6:7], v[6:7], v[78:79]
	v_pk_mul_f32 v[4:5], v[4:5], v[76:77]
	ds_write2st64_b32 v68, v52, v53 offset1:1
	ds_write2st64_b32 v68, v54, v55 offset0:2 offset1:3
	ds_write2st64_b32 v68, v56, v57 offset0:8 offset1:9
	ds_write2st64_b32 v68, v58, v59 offset0:10 offset1:11
	ds_write2st64_b32 v68, v60, v61 offset0:16 offset1:17
	ds_write2st64_b32 v68, v62, v63 offset0:18 offset1:19
	ds_write2st64_b32 v68, v64, v65 offset0:24 offset1:25
	ds_write2st64_b32 v68, v66, v67 offset0:26 offset1:27
	s_branch .LBB0_315
.Lcs_early:
	v_mov_b32_e32 v80, 0
	v_mov_b32_e32 v81, 0
	v_mov_b32_e32 v82, 0
	v_mov_b32_e32 v83, 0
	s_mov_b32 s0, 0
	s_andn2_b64 vcc, exec, s[58:59]
	s_cbranch_vccnz .Lcs_rem
	v_mov_b32_e32 v109, v183
.Lcs_loop:
	ds_read_b128 v[104:107], v109
	ds_read_b128 v[110:113], v109 offset:256
	ds_read_b128 v[114:117], v109 offset:512
	ds_read_b128 v[226:229], v109 offset:768
	ds_read_b128 v[230:233], v109 offset:1024
	ds_read_b128 v[234:237], v109 offset:1280
	ds_read_b128 v[238:241], v109 offset:1536
	ds_read_b128 v[242:245], v109 offset:1792
	s_add_i32 s0, s0, 2
	s_cmp_eq_u32 s64, s0
	v_add_u32_e32 v109, 0x800, v109
	s_waitcnt lgkmcnt(4)
	v_pk_add_f32 v[248:249], v[106:107], v[112:113]
	v_pk_add_f32 v[104:105], v[104:105], v[110:111]
	v_pk_add_f32 v[106:107], v[116:117], v[228:229]
	v_pk_add_f32 v[110:111], v[114:115], v[226:227]
	v_pk_add_f32 v[248:249], v[248:249], v[106:107]
	v_pk_add_f32 v[104:105], v[104:105], v[110:111]
	v_pk_add_f32 v[248:249], v[82:83], v[248:249]
	v_pk_add_f32 v[118:119], v[80:81], v[104:105]
	s_waitcnt lgkmcnt(0)
	v_pk_add_f32 v[82:83], v[232:233], v[236:237]
	v_pk_add_f32 v[80:81], v[230:231], v[234:235]
	v_pk_add_f32 v[104:105], v[240:241], v[244:245]
	v_pk_add_f32 v[106:107], v[238:239], v[242:243]
	v_pk_add_f32 v[82:83], v[82:83], v[104:105]
	v_pk_add_f32 v[80:81], v[80:81], v[106:107]
	v_pk_add_f32 v[82:83], v[248:249], v[82:83]
	v_pk_add_f32 v[80:81], v[118:119], v[80:81]
	s_cbranch_scc0 .Lcs_loop
	s_lshl_b32 s0, s64, 10
.Lcs_rem:
	v_add_u32_e32 v109, s92, v162
	v_add_u32_e32 v246, s81, v162
	v_add_u32_e32 v247, s20, v162
	s_andn2_b64 vcc, exec, s[2:3]
	s_cbranch_vccnz .Lcs_own
	v_add_u32_e32 v248, s0, v162
	ds_read_b128 v[104:107], v248 offset:24576
	ds_read_b128 v[110:113], v248 offset:24832
	ds_read_b128 v[114:117], v248 offset:25088
	ds_read_b128 v[226:229], v248 offset:25344
	ds_read_b128 v[242:245], v109 offset:24576
	ds_read_b128 v[230:233], v109 offset:24832
	ds_read_b128 v[234:237], v246 offset:24576
	ds_read_b128 v[238:241], v247 offset:24576
	s_waitcnt lgkmcnt(4)
	v_pk_add_f32 v[248:249], v[106:107], v[112:113]
	v_pk_add_f32 v[104:105], v[104:105], v[110:111]
	v_pk_add_f32 v[106:107], v[116:117], v[228:229]
	v_pk_add_f32 v[110:111], v[114:115], v[226:227]
	v_pk_add_f32 v[248:249], v[248:249], v[106:107]
	v_pk_add_f32 v[104:105], v[104:105], v[110:111]
	v_pk_add_f32 v[82:83], v[82:83], v[248:249]
	v_pk_add_f32 v[80:81], v[80:81], v[104:105]
	s_branch .Lcs_sum
.Lcs_own:
	ds_read_b128 v[242:245], v109 offset:24576
	ds_read_b128 v[230:233], v109 offset:24832
	ds_read_b128 v[234:237], v246 offset:24576
	ds_read_b128 v[238:241], v247 offset:24576
.Lcs_sum:
	s_mov_b64 s[0:1], exec
	s_waitcnt lgkmcnt(0)
	s_and_b64 exec, s[0:1], s[12:13]
	v_pk_add_f32 v[82:83], v[82:83], v[244:245]
	v_pk_add_f32 v[80:81], v[80:81], v[242:243]
	s_and_b64 exec, s[0:1], s[14:15]
	v_pk_add_f32 v[82:83], v[82:83], v[232:233]
	v_pk_add_f32 v[80:81], v[80:81], v[230:231]
	s_and_b64 exec, s[0:1], s[16:17]
	v_pk_add_f32 v[82:83], v[82:83], v[236:237]
	v_pk_add_f32 v[80:81], v[80:81], v[234:235]
	s_and_b64 exec, s[0:1], s[18:19]
	v_pk_add_f32 v[82:83], v[82:83], v[240:241]
	v_pk_add_f32 v[80:81], v[80:81], v[238:239]
	s_mov_b64 exec, s[0:1]
